# down-projection residual epilogue: four residual loads in flight per wave instead of one (distinct registers, counted vmcnt)
# speedup vs baseline: 1.0195x; 1.0042x over previous
;     __device__ __forceinline__ void fused(f32x4 (&acc)[2][2][4][2], const Unit& u, int wr, int wc, int fr, int fq, PG8_LAS unsigned char* lds, int wid, int lane) const {
;         const int row0 = u.pm * BM + wr * 64 + fr, col0 = u.pn * BM + wc * 32 + 4 * fq; const int bo = (u.pm >= 32 ? 9216 : 0); const float* gp = gate + bo + col0;
;         f32x4 gv[2][2];
; #pragma unroll
;         for (int bj = 0; bj < 2; ++bj)
; #pragma unroll
;             for (int n = 0; n < 2; ++n) gv[bj][n] = *(const f32x4*)(gp + bj * HALF + n * 16) * coef;
; #pragma unroll
;         for (int ai = 0; ai < 2; ++ai)
; #pragma unroll
;             for (int m = 0; m < 4; ++m) { const size_t off = (size_t)(row0 + ai * HALF + m * 16) * 1024 + col0;
; #pragma unroll
;                 for (int bj = 0; bj < 2; ++bj)
; #pragma unroll
;                     for (int n = 0; n < 2; ++n) { const f32x4 bs = *(const f32x4*)(base + off + bj * HALF + n * 16); acc[ai][bj][m][n] = bs + gv[bj][n] * acc[ai][bj][m][n]; *(f32x4*)(out + off + bj * HALF + n * 16) = acc[ai][bj][m][n]; }
;                 if (m & 1) asm volatile("" ::: "memory"); }
.LBB0_387:
	v_readlane_b32 s0, v255, 17
	v_readlane_b32 s1, v255, 18
	s_and_b64 s[4:5], s[0:1], s[12:13]
	v_readlane_b32 s0, v255, 13
	s_or_b32 s0, s3, s0
	s_cmp_eq_u32 s0, 0
	v_readlane_b32 s0, v255, 21
	v_readlane_b32 s1, v255, 22
	s_cselect_b32 s7, s23, s21
	s_cselect_b32 s6, s22, s20
	s_lshl_b64 s[0:1], s[0:1], 2
	s_add_u32 s8, s14, s0
	s_addc_u32 s9, s15, s1
	s_and_b64 s[0:1], s[12:13], exec
	s_movk_i32 s0, 0x2000
	s_cselect_b32 s0, 0x8000, s0
	s_add_u32 s8, s8, s0
	s_addc_u32 s9, s9, 0
	s_lshl_b32 s1, s38, 5
	s_lshl_b32 s0, s37, 8
	s_lshl_b32 s23, s18, 8
	s_add_i32 s22, s0, s49
	s_or_b32 s1, s23, s1
	v_lshrrev_b32_e32 v0, 2, v153
	s_cmp_gt_i32 s37, 31
	v_and_or_b32 v140, v0, 12, s1
	s_cselect_b32 s1, 0x2400, 0
	s_lshl_b32 s1, s1, 2
	s_add_u32 s8, s8, s1
	s_addc_u32 s9, s9, 0
	v_ashrrev_i32_e32 v141, 31, v140
	v_lshl_add_u64 v[150:151], v[140:141], 2, s[8:9]
	s_barrier
	global_load_dwordx4 v[130:133], v[150:151], off
	global_load_dwordx4 v[154:157], v[150:151], off offset:576
	s_mov_b64 s[8:9], 0x80000
	s_and_b64 vcc, exec, s[4:5]
	s_movk_i32 s58, 0x7fff
	s_mov_b32 s59, 0xffff0000
	s_mov_b64 s[60:61], 0x1000
	s_waitcnt vmcnt(0)
	v_pk_mul_f32 v[144:145], v[132:133], 0.5 op_sel_hi:[1,0]
	v_pk_mul_f32 v[146:147], v[130:131], 0.5 op_sel_hi:[1,0]
	global_load_dwordx4 v[130:133], v[150:151], off offset:64
	s_waitcnt vmcnt(0)
	v_pk_mul_f32 v[138:139], v[132:133], 0.5 op_sel_hi:[1,0]
	v_pk_mul_f32 v[142:143], v[130:131], 0.5 op_sel_hi:[1,0]
	global_load_dwordx4 v[130:133], v[150:151], off offset:512
	v_or_b32_e32 v150, s22, v148
	v_ashrrev_i32_e32 v151, 31, v150
	v_lshlrev_b64 v[148:149], 10, v[150:151]
	v_lshl_add_u64 v[148:149], v[148:149], 0, v[140:141]
	v_lshlrev_b64 v[148:149], 2, v[148:149]
	v_lshl_add_u64 v[158:159], s[6:7], 0, v[148:149]
	v_lshl_add_u64 v[160:161], s[20:21], 0, v[148:149]
	s_waitcnt vmcnt(0)
	v_pk_mul_f32 v[134:135], v[132:133], 0.5 op_sel_hi:[1,0]
	v_pk_mul_f32 v[136:137], v[130:131], 0.5 op_sel_hi:[1,0]
	v_pk_mul_f32 v[130:131], v[156:157], 0.5 op_sel_hi:[1,0]
	v_pk_mul_f32 v[132:133], v[154:155], 0.5 op_sel_hi:[1,0]
	global_load_dwordx4 v[170:173], v[158:159], off
	global_load_dwordx4 v[174:177], v[158:159], off offset:64
	global_load_dwordx4 v[178:181], v[158:159], off offset:512
	global_load_dwordx4 v[182:185], v[158:159], off offset:576
	s_waitcnt vmcnt(3)
	v_pk_fma_f32 v[116:117], v[116:117], v[144:145], v[172:173]
	v_pk_fma_f32 v[114:115], v[114:115], v[146:147], v[170:171]
	global_store_dwordx4 v[160:161], v[114:117], off
	s_waitcnt vmcnt(3)
	v_pk_fma_f32 v[84:85], v[84:85], v[138:139], v[176:177]
	v_pk_fma_f32 v[82:83], v[82:83], v[142:143], v[174:175]
	global_store_dwordx4 v[160:161], v[82:85], off offset:64
	s_waitcnt vmcnt(3)
	v_pk_fma_f32 v[28:29], v[28:29], v[134:135], v[180:181]
	v_pk_fma_f32 v[26:27], v[26:27], v[136:137], v[178:179]
	global_store_dwordx4 v[160:161], v[26:29], off offset:512
	s_waitcnt vmcnt(3)
	v_pk_fma_f32 v[2:3], v[2:3], v[132:133], v[182:183]
	v_or_b32_e32 v154, 16, v150
	v_ashrrev_i32_e32 v155, 31, v154
	v_lshlrev_b64 v[154:155], 10, v[154:155]
	v_lshl_add_u64 v[154:155], v[154:155], 0, v[140:141]
	v_pk_fma_f32 v[4:5], v[4:5], v[130:131], v[184:185]
	v_lshlrev_b64 v[158:159], 2, v[154:155]
	global_store_dwordx4 v[160:161], v[2:5], off offset:576
	v_lshl_add_u64 v[160:161], s[6:7], 0, v[158:159]
	global_load_dwordx4 v[170:173], v[160:161], off
	global_load_dwordx4 v[174:177], v[160:161], off offset:64
	global_load_dwordx4 v[178:181], v[160:161], off offset:512
	global_load_dwordx4 v[182:185], v[160:161], off offset:576
	v_lshl_add_u64 v[158:159], s[20:21], 0, v[158:159]
	s_waitcnt vmcnt(3)
	v_pk_fma_f32 v[124:125], v[124:125], v[144:145], v[172:173]
	v_pk_fma_f32 v[122:123], v[122:123], v[146:147], v[170:171]
	global_store_dwordx4 v[158:159], v[122:125], off
	s_waitcnt vmcnt(3)
	v_pk_fma_f32 v[96:97], v[96:97], v[138:139], v[176:177]
	v_pk_fma_f32 v[94:95], v[94:95], v[142:143], v[174:175]
	global_store_dwordx4 v[158:159], v[94:97], off offset:64
	s_waitcnt vmcnt(3)
	v_pk_fma_f32 v[36:37], v[36:37], v[134:135], v[180:181]
	v_pk_fma_f32 v[34:35], v[34:35], v[136:137], v[178:179]
	global_store_dwordx4 v[158:159], v[34:37], off offset:512
	s_waitcnt vmcnt(3)
	v_pk_fma_f32 v[6:7], v[6:7], v[132:133], v[182:183]
	v_or_b32_e32 v154, 32, v150
	v_ashrrev_i32_e32 v155, 31, v154
	v_lshlrev_b64 v[154:155], 10, v[154:155]
	v_pk_fma_f32 v[8:9], v[8:9], v[130:131], v[184:185]
	v_lshl_add_u64 v[154:155], v[154:155], 0, v[140:141]
	global_store_dwordx4 v[158:159], v[6:9], off offset:576
	v_lshlrev_b64 v[158:159], 2, v[154:155]
	v_lshl_add_u64 v[160:161], s[6:7], 0, v[158:159]
	global_load_dwordx4 v[170:173], v[160:161], off
	global_load_dwordx4 v[174:177], v[160:161], off offset:64
	global_load_dwordx4 v[178:181], v[160:161], off offset:512
	global_load_dwordx4 v[182:185], v[160:161], off offset:576
	v_lshl_add_u64 v[158:159], s[20:21], 0, v[158:159]
	v_or_b32_e32 v150, 48, v150
	v_ashrrev_i32_e32 v151, 31, v150
	v_lshlrev_b64 v[150:151], 10, v[150:151]
	v_lshl_add_u64 v[150:151], v[150:151], 0, v[140:141]
	v_lshlrev_b64 v[150:151], 2, v[150:151]
	s_waitcnt vmcnt(3)
	v_pk_fma_f32 v[128:129], v[128:129], v[144:145], v[172:173]
	v_pk_fma_f32 v[126:127], v[126:127], v[146:147], v[170:171]
	global_store_dwordx4 v[158:159], v[126:129], off
	s_waitcnt vmcnt(3)
	v_pk_fma_f32 v[108:109], v[108:109], v[138:139], v[176:177]
	v_pk_fma_f32 v[106:107], v[106:107], v[142:143], v[174:175]
	global_store_dwordx4 v[158:159], v[106:109], off offset:64
	s_waitcnt vmcnt(3)
	v_pk_fma_f32 v[44:45], v[44:45], v[134:135], v[180:181]
	v_pk_fma_f32 v[42:43], v[42:43], v[136:137], v[178:179]
	global_store_dwordx4 v[158:159], v[42:45], off offset:512
	s_waitcnt vmcnt(3)
;     __device__ __forceinline__ void fused(f32x4 (&acc)[2][2][4][2], const Unit& u, int wr, int wc, int fr, int fq, PG8_LAS unsigned char* lds, int wid, int lane) const {
;     ...
;             for (int m = 0; m < 4; ++m) { const size_t off = (size_t)(row0 + ai * HALF + m * 16) * 1024 + col0;
; #pragma unroll
;                 for (int bj = 0; bj < 2; ++bj)
; #pragma unroll
;                     for (int n = 0; n < 2; ++n) { const f32x4 bs = *(const f32x4*)(base + off + bj * HALF + n * 16); acc[ai][bj][m][n] = bs + gv[bj][n] * acc[ai][bj][m][n]; *(f32x4*)(out + off + bj * HALF + n * 16) = acc[ai][bj][m][n]; }
;                 if (m & 1) asm volatile("" ::: "memory"); }
	v_pk_fma_f32 v[12:13], v[12:13], v[130:131], v[184:185]
	v_pk_fma_f32 v[10:11], v[10:11], v[132:133], v[182:183]
	global_store_dwordx4 v[158:159], v[10:13], off offset:576
	v_lshl_add_u64 v[158:159], s[6:7], 0, v[150:151]
	global_load_dwordx4 v[170:173], v[158:159], off
	global_load_dwordx4 v[174:177], v[158:159], off offset:64
	global_load_dwordx4 v[178:181], v[158:159], off offset:512
	global_load_dwordx4 v[182:185], v[158:159], off offset:576
	v_lshl_add_u64 v[150:151], s[20:21], 0, v[150:151]
	s_waitcnt vmcnt(3)
	v_pk_fma_f32 v[120:121], v[120:121], v[144:145], v[172:173]
	v_pk_fma_f32 v[118:119], v[118:119], v[146:147], v[170:171]
	global_store_dwordx4 v[150:151], v[118:121], off
	s_waitcnt vmcnt(3)
	v_pk_fma_f32 v[112:113], v[112:113], v[138:139], v[176:177]
	v_pk_fma_f32 v[110:111], v[110:111], v[142:143], v[174:175]
	global_store_dwordx4 v[150:151], v[110:113], off offset:64
	s_waitcnt vmcnt(3)
	v_pk_fma_f32 v[48:49], v[48:49], v[134:135], v[180:181]
	v_pk_fma_f32 v[46:47], v[46:47], v[136:137], v[178:179]
	global_store_dwordx4 v[150:151], v[46:49], off offset:512
	s_waitcnt vmcnt(3)
	v_pk_fma_f32 v[16:17], v[16:17], v[130:131], v[184:185]
	v_pk_fma_f32 v[14:15], v[14:15], v[132:133], v[182:183]
	global_store_dwordx4 v[150:151], v[14:17], off offset:576
	v_lshl_add_u64 v[150:151], v[148:149], 0, s[8:9]
	v_lshl_add_u64 v[158:159], s[6:7], 0, v[150:151]
	global_load_dwordx4 v[170:173], v[158:159], off
	global_load_dwordx4 v[174:177], v[158:159], off offset:64
	global_load_dwordx4 v[178:181], v[158:159], off offset:512
	global_load_dwordx4 v[182:185], v[158:159], off offset:576
	v_lshl_add_u64 v[150:151], s[20:21], 0, v[150:151]
	s_mov_b64 s[8:9], 0x90000
	s_waitcnt vmcnt(3)
	v_pk_fma_f32 v[104:105], v[104:105], v[144:145], v[172:173]
	v_pk_fma_f32 v[102:103], v[102:103], v[146:147], v[170:171]
	global_store_dwordx4 v[150:151], v[102:105], off
	s_waitcnt vmcnt(3)
	v_pk_fma_f32 v[100:101], v[100:101], v[138:139], v[176:177]
	v_pk_fma_f32 v[98:99], v[98:99], v[142:143], v[174:175]
	global_store_dwordx4 v[150:151], v[98:101], off offset:64
	s_waitcnt vmcnt(3)
	v_pk_fma_f32 v[56:57], v[56:57], v[134:135], v[180:181]
	v_pk_fma_f32 v[54:55], v[54:55], v[136:137], v[178:179]
	global_store_dwordx4 v[150:151], v[54:57], off offset:512
	s_waitcnt vmcnt(3)
	v_pk_fma_f32 v[20:21], v[20:21], v[130:131], v[184:185]
	v_pk_fma_f32 v[18:19], v[18:19], v[132:133], v[182:183]
	global_store_dwordx4 v[150:151], v[18:21], off offset:576
	v_lshl_add_u64 v[150:151], v[148:149], 0, s[8:9]
	v_lshl_add_u64 v[158:159], s[6:7], 0, v[150:151]
	global_load_dwordx4 v[170:173], v[158:159], off
	global_load_dwordx4 v[174:177], v[158:159], off offset:64
	global_load_dwordx4 v[178:181], v[158:159], off offset:512
	global_load_dwordx4 v[182:185], v[158:159], off offset:576
	v_lshl_add_u64 v[150:151], s[20:21], 0, v[150:151]
	s_mov_b64 s[8:9], 0xa0000
	s_waitcnt vmcnt(3)
	v_pk_fma_f32 v[92:93], v[92:93], v[144:145], v[172:173]
	v_pk_fma_f32 v[90:91], v[90:91], v[146:147], v[170:171]
	global_store_dwordx4 v[150:151], v[90:93], off
	s_waitcnt vmcnt(3)
	v_pk_fma_f32 v[88:89], v[88:89], v[138:139], v[176:177]
	v_pk_fma_f32 v[86:87], v[86:87], v[142:143], v[174:175]
	global_store_dwordx4 v[150:151], v[86:89], off offset:64
	s_waitcnt vmcnt(3)
	v_pk_fma_f32 v[60:61], v[60:61], v[134:135], v[180:181]
	v_pk_fma_f32 v[58:59], v[58:59], v[136:137], v[178:179]
	global_store_dwordx4 v[150:151], v[58:61], off offset:512
	s_waitcnt vmcnt(3)
	v_pk_fma_f32 v[32:33], v[32:33], v[130:131], v[184:185]
	v_pk_fma_f32 v[30:31], v[30:31], v[132:133], v[182:183]
	global_store_dwordx4 v[150:151], v[30:33], off offset:576
	v_lshl_add_u64 v[150:151], v[148:149], 0, s[8:9]
	v_lshl_add_u64 v[158:159], s[6:7], 0, v[150:151]
	global_load_dwordx4 v[170:173], v[158:159], off
	global_load_dwordx4 v[174:177], v[158:159], off offset:64
	global_load_dwordx4 v[178:181], v[158:159], off offset:512
	global_load_dwordx4 v[182:185], v[158:159], off offset:576
	v_lshl_add_u64 v[150:151], s[20:21], 0, v[150:151]
	s_mov_b64 s[8:9], 0xb0000
	s_waitcnt vmcnt(3)
	v_pk_fma_f32 v[80:81], v[80:81], v[144:145], v[172:173]
	v_pk_fma_f32 v[78:79], v[78:79], v[146:147], v[170:171]
	global_store_dwordx4 v[150:151], v[78:81], off
	s_waitcnt vmcnt(3)
	v_pk_fma_f32 v[76:77], v[76:77], v[138:139], v[176:177]
	v_pk_fma_f32 v[74:75], v[74:75], v[142:143], v[174:175]
	global_store_dwordx4 v[150:151], v[74:77], off offset:64
	s_waitcnt vmcnt(3)
	v_pk_fma_f32 v[64:65], v[64:65], v[134:135], v[180:181]
	v_pk_fma_f32 v[62:63], v[62:63], v[136:137], v[178:179]
	global_store_dwordx4 v[150:151], v[62:65], off offset:512
	s_waitcnt vmcnt(3)
	v_pk_fma_f32 v[40:41], v[40:41], v[130:131], v[184:185]
	v_pk_fma_f32 v[38:39], v[38:39], v[132:133], v[182:183]
	v_lshl_add_u64 v[154:155], v[148:149], 0, s[8:9]
	global_store_dwordx4 v[150:151], v[38:41], off offset:576
	v_lshl_add_u64 v[156:157], s[6:7], 0, v[154:155]
	global_load_dwordx4 v[170:173], v[156:157], off
	global_load_dwordx4 v[174:177], v[156:157], off offset:64
	global_load_dwordx4 v[178:181], v[156:157], off offset:512
	global_load_dwordx4 v[182:185], v[156:157], off offset:576
	s_waitcnt vmcnt(3)
	v_pk_fma_f32 v[72:73], v[72:73], v[144:145], v[172:173]
	v_pk_fma_f32 v[70:71], v[70:71], v[146:147], v[170:171]
	v_lshl_add_u64 v[148:149], s[20:21], 0, v[154:155]
	global_store_dwordx4 v[148:149], v[70:73], off
	s_waitcnt vmcnt(3)
	v_pk_fma_f32 v[68:69], v[68:69], v[138:139], v[176:177]
	v_pk_fma_f32 v[66:67], v[66:67], v[142:143], v[174:175]
	global_store_dwordx4 v[148:149], v[66:69], off offset:64
	s_waitcnt vmcnt(3)
	v_pk_fma_f32 v[52:53], v[52:53], v[134:135], v[180:181]
	v_pk_fma_f32 v[50:51], v[50:51], v[136:137], v[178:179]
	global_store_dwordx4 v[148:149], v[50:53], off offset:512
	s_waitcnt vmcnt(3)
	v_pk_fma_f32 v[24:25], v[24:25], v[130:131], v[184:185]
	v_pk_fma_f32 v[22:23], v[22:23], v[132:133], v[182:183]
	global_store_dwordx4 v[148:149], v[22:25], off offset:576
	s_cbranch_vccnz .LBB0_425
;     __device__ __forceinline__ void fused(f32x4 (&acc)[2][2][4][2], const Unit& u, int wr, int wc, int fr, int fq, PG8_LAS unsigned char* lds, int wid, int lane) const {
;     ...
;         for (int ai = 0; ai < 2; ++ai)
; #pragma unroll
;             for (int m = 0; m < 4; ++m) { float q = 0.f;
; #pragma unroll
;                 for (int bj = 0; bj < 2; ++bj)
; #pragma unroll
;                     for (int n = 0; n < 2; ++n) { const f32x4 x = acc[ai][bj][m][n]; q += (x[0] * x[0] + x[1] * x[1]) + (x[2] * x[2] + x[3] * x[3]); }
;                 q += __shfl_xor(q, 16); q += __shfl_xor(q, 32);
;                 if (fq == 0) P[(ai * HALF + wr * 64 + m * 16 + fr) * 4 + wc] = q; }
	v_mul_f32_e32 v132, v115, v115
	v_mul_f32_e32 v133, v117, v117
	v_fmac_f32_e32 v132, v114, v114
	v_fmac_f32_e32 v133, v116, v116
	v_add_f32_e32 v132, v132, v133
	v_mul_f32_e32 v133, v83, v83
	v_mul_f32_e32 v134, v85, v85
	v_fmac_f32_e32 v133, v82, v82
	v_fmac_f32_e32 v134, v84, v84
	v_add_f32_e32 v133, v133, v134
	v_add_f32_e32 v132, v132, v133
	v_mul_f32_e32 v133, v27, v27
	v_mul_f32_e32 v134, v29, v29
	v_fmac_f32_e32 v133, v26, v26
	v_fmac_f32_e32 v134, v28, v28
	v_and_b32_e32 v131, 64, v240
	v_add_f32_e32 v133, v133, v134
	v_xor_b32_e32 v130, 16, v240
	v_add_u32_e32 v131, 64, v131
	v_add_f32_e32 v132, v132, v133
	v_mul_f32_e32 v133, v3, v3
	v_mul_f32_e32 v134, v5, v5
	v_cmp_lt_i32_e32 vcc, v130, v131
	v_fmac_f32_e32 v133, v2, v2
	v_fmac_f32_e32 v134, v4, v4
	v_cndmask_b32_e32 v130, v240, v130, vcc
	v_add_f32_e32 v133, v133, v134
	v_lshlrev_b32_e32 v130, 2, v130
	v_add_f32_e32 v133, v132, v133
	ds_bpermute_b32 v134, v130, v133
	v_xor_b32_e32 v132, 32, v240
	v_cmp_lt_i32_e32 vcc, v132, v131
	s_lshl_b32 s4, s38, 2
	v_and_b32_e32 v0, 63, v153
	v_cndmask_b32_e32 v131, v240, v132, vcc
	v_lshlrev_b32_e32 v132, 2, v131
	s_waitcnt lgkmcnt(0)
	v_add_f32_e32 v133, v133, v134
	ds_bpermute_b32 v134, v132, v133
	s_add_i32 s4, s4, 0
	v_cmp_gt_u32_e32 vcc, 16, v0
	v_lshl_add_u32 v131, v152, 4, s4
	s_and_saveexec_b64 s[4:5], vcc
	s_cbranch_execz .LBB0_390
	s_waitcnt lgkmcnt(0)
	v_add_f32_e32 v133, v133, v134
	ds_write_b32 v131, v133
